# attention: next-tile prefetch address block placed right after the last QK MFMA (fills the MFMA-to-VALU wait, s_nop 6 dropped)
# speedup vs baseline: 1.0265x; 1.0059x over previous
; #define LAS __attribute__((address_space(3)))
; __device__ __forceinline__ void qk_tile(f32x16& s0, f32x16& s1, LAS unsigned char* kb, const bf16x8 (&qr)[6], const f32x16& negm, int r32, int hi) {
;     bf16x8 kf[12];
; #pragma unroll
;     for (int ks = 0; ks < 6; ++ks) { kf[2 * ks] = *(const LAS bf16x8*)(kb + r32 * KPT + ks * 32 + hi * 16); kf[2 * ks + 1] = *(const LAS bf16x8*)(kb + (32 + r32) * KPT + ks * 32 + hi * 16); }
;     __builtin_amdgcn_sched_barrier(0);
; #pragma unroll
;     for (int ks = 0; ks < 6; ++ks) {
;         s0 = __builtin_amdgcn_mfma_f32_32x32x16_bf16(kf[2 * ks], qr[ks], ks == 0 ? negm : s0, 0, 0, 0);
;         s1 = __builtin_amdgcn_mfma_f32_32x32x16_bf16(kf[2 * ks + 1], qr[ks], ks == 0 ? negm : s1, 0, 0, 0);
;     }
; }
; __device__ __forceinline__ void sm_pv(f32x16& s0, f32x16& s1, f32x16& o0, f32x16& o1, float& m_run, float& l_run, f32x16& negm, LAS unsigned char* vb, bool domask, int kbase, int qm, int r32, int hi) {
;     s16x4 vlo[8], vhh[8];
; #pragma unroll
;     for (int kk = 0; kk < 4; ++kk) { const int koff = 2 * (16 * kk + 4 * hi);
;         vlo[2 * kk] = *(const LAS s16x4*)(vb + r32 * VP + koff); vhh[2 * kk] = *(const LAS s16x4*)(vb + r32 * VP + koff + 16);
;         vlo[2 * kk + 1] = *(const LAS s16x4*)(vb + (32 + r32) * VP + koff); vhh[2 * kk + 1] = *(const LAS s16x4*)(vb + (32 + r32) * VP + koff + 16); }
;     __builtin_amdgcn_sched_barrier(0);
;     if (domask) {
;         const int kb0 = kbase + 4 * hi;
; #pragma unroll
;         for (int r = 0; r < 16; ++r) { const int kv = kb0 + (r & 3) + 8 * (r >> 2); if (kv > qm) s0[r] = -INFINITY; if (kv + 32 > qm) s1[r] = -INFINITY; }
;     }
.LBB0_418:
	s_add_i32 s85, s84, -3
	s_cmp_lt_u32 s85, s57
	s_cselect_b64 s[44:45], -1, 0
	s_and_b64 s[4:5], s[44:45], exec
	s_cselect_b32 s4, 0, s79
	s_lshl_b32 s4, s4, 6
	v_add_u32_e32 v221, s83, v213
	v_add_u32_e32 v222, s83, v173
	s_sub_i32 s5, 0x80, s4
	v_cmp_le_u32_e32 vcc, s83, v220
	s_and_saveexec_b64 s[46:47], vcc
	s_cbranch_execz .Latt_sk1
	ds_read_b128 v[10:13], v240 offset:13312
	ds_read_b128 v[136:139], v240 offset:13344
	ds_read_b128 v[140:143], v240 offset:19968
	ds_read_b128 v[144:147], v240 offset:20000
	ds_read_b128 v[148:151], v240 offset:13376
	ds_read_b128 v[152:155], v240 offset:13408
	ds_read_b128 v[156:159], v240 offset:20032
	ds_read_b128 v[160:163], v240 offset:20064
	ds_read_b128 v[224:227], v240 offset:13440
	ds_read_b128 v[228:231], v240 offset:13472
	ds_read_b128 v[232:235], v240 offset:20096
	ds_read_b128 v[246:249], v240 offset:20128
	s_waitcnt lgkmcnt(11)
	v_mfma_f32_32x32x16_bf16 v[80:95], v[10:13], v[96:99], v[48:63]
	s_add_i32 s4, s83, 63
	v_cmp_gt_i32_e32 vcc, s4, v175
	s_waitcnt lgkmcnt(9)
	v_mfma_f32_32x32x16_bf16 v[64:79], v[140:143], v[96:99], v[48:63]
	v_mfma_f32_32x32x16_bf16 v[80:95], v[136:139], v[100:103], v[80:95]
	s_waitcnt lgkmcnt(8)
	v_mfma_f32_32x32x16_bf16 v[64:79], v[144:147], v[100:103], v[64:79]
	s_waitcnt lgkmcnt(7)
	v_mfma_f32_32x32x16_bf16 v[80:95], v[148:151], v[104:107], v[80:95]
	s_waitcnt lgkmcnt(5)
	v_mfma_f32_32x32x16_bf16 v[64:79], v[156:159], v[104:107], v[64:79]
	v_mfma_f32_32x32x16_bf16 v[80:95], v[152:155], v[108:111], v[80:95]
	ds_read2_b64 v[152:155], v250 offset0:68 offset1:70
	s_waitcnt lgkmcnt(5)
	v_mfma_f32_32x32x16_bf16 v[64:79], v[160:163], v[108:111], v[64:79]
	ds_read2_b64 v[160:163], v250 offset0:64 offset1:66
	ds_read2_b64 v[156:159], v251 offset0:96 offset1:98
	ds_read2_b64 v[148:151], v251 offset0:100 offset1:102
	ds_read2_b64 v[144:147], v250 offset0:72 offset1:74
	ds_read2_b64 v[140:143], v251 offset0:104 offset1:106
	ds_read2_b64 v[136:139], v250 offset0:76 offset1:78
	ds_read2_b64 v[10:13], v251 offset0:108 offset1:110
	s_waitcnt lgkmcnt(11)
	v_mfma_f32_32x32x16_bf16 v[80:95], v[224:227], v[112:115], v[80:95]
	s_waitcnt lgkmcnt(9)
	v_mfma_f32_32x32x16_bf16 v[64:79], v[232:235], v[112:115], v[64:79]
	v_mfma_f32_32x32x16_bf16 v[80:95], v[228:231], v[116:119], v[80:95]
	s_waitcnt lgkmcnt(8)
	v_mfma_f32_32x32x16_bf16 v[64:79], v[246:249], v[116:119], v[64:79]
	s_waitcnt vmcnt(3)
	v_add_u32_e32 v2, s5, v221
	v_add_u32_e32 v14, s5, v222
	v_min_u32_e32 v2, 0x80ff, v2
	v_add_u32_e32 v192, 1, v14
	v_min_u32_e32 v14, 0x80ff, v14
	v_min_u32_e32 v192, 0x80ff, v192
	v_lshl_add_u32 v4, v2, 12, v238
	s_waitcnt vmcnt(2)
	v_lshl_add_u32 v6, v2, 6, v239
	v_lshl_add_u32 v14, v14, 12, v174
	v_lshl_add_u32 v192, v192, 12, v174
	global_load_dwordx4 v[2:5], v4, s[98:99]
	s_nop 0
	global_load_dwordx4 v[6:9], v6, s[100:101]
	global_load_dwordx2 v[14:15], v14, s[98:99] offset:128
	global_load_dwordx2 v[192:193], v192, s[98:99] offset:128
	s_and_saveexec_b64 s[58:59], vcc
	s_cbranch_execz .LBB0_423
	v_add_u32_e32 v223, s83, v201
	v_add_u32_e32 v224, 32, v223
	v_cmp_ge_i32_e64 s[4:5], v177, v224
	v_add_u32_e32 v224, 33, v223
	v_cmp_ge_i32_e64 s[6:7], v177, v224
	v_add_u32_e32 v224, 2, v223
	v_cmp_le_u32_e32 vcc, v223, v219
	s_nop 2
	v_cndmask_b32_e64 v65, v244, v65, s[6:7]
	v_cmp_ge_i32_e64 s[6:7], v177, v224
	v_add_u32_e32 v224, 34, v223
	v_cmp_ge_i32_e64 s[8:9], v177, v224
	v_add_u32_e32 v224, 3, v223
	v_cndmask_b32_e64 v64, v244, v64, s[4:5]
	v_cndmask_b32_e64 v66, v244, v66, s[8:9]
	v_cmp_ge_i32_e64 s[8:9], v177, v224
	v_add_u32_e32 v224, 35, v223
	v_cmp_ge_i32_e64 s[10:11], v177, v224
	v_add_u32_e32 v224, 8, v223
	v_cmp_gt_i32_e64 s[4:5], v177, v223
	v_cndmask_b32_e64 v67, v244, v67, s[10:11]
	v_cmp_ge_i32_e64 s[10:11], v177, v224
	v_add_u32_e32 v224, 40, v223
	v_cmp_ge_i32_e64 s[12:13], v177, v224
	v_add_u32_e32 v224, 9, v223
	s_nop 0
	v_cndmask_b32_e64 v68, v244, v68, s[12:13]
	v_cmp_ge_i32_e64 s[12:13], v177, v224
	v_add_u32_e32 v224, 41, v223
	v_cmp_ge_i32_e64 s[14:15], v177, v224
	v_add_u32_e32 v224, 10, v223
	s_nop 0
	v_cndmask_b32_e64 v69, v244, v69, s[14:15]
	v_cmp_ge_i32_e64 s[14:15], v177, v224
	v_add_u32_e32 v224, 42, v223
	v_cmp_ge_i32_e64 s[16:17], v177, v224
	v_add_u32_e32 v224, 11, v223
	s_nop 0
	v_cndmask_b32_e64 v70, v244, v70, s[16:17]
	v_cmp_ge_i32_e64 s[16:17], v177, v224
	v_add_u32_e32 v224, 43, v223
	v_cmp_ge_i32_e64 s[18:19], v177, v224
	v_add_u32_e32 v224, 16, v223
	s_nop 0
	v_cndmask_b32_e64 v71, v244, v71, s[18:19]
	v_cmp_ge_i32_e64 s[18:19], v177, v224
	v_add_u32_e32 v224, 48, v223
	v_cmp_ge_i32_e64 s[20:21], v177, v224
	v_add_u32_e32 v224, 17, v223
	s_nop 0
	v_cndmask_b32_e64 v72, v244, v72, s[20:21]
	v_cmp_ge_i32_e64 s[20:21], v177, v224
	v_add_u32_e32 v224, 49, v223
	v_cmp_ge_i32_e64 s[22:23], v177, v224
	v_add_u32_e32 v224, 18, v223
	s_nop 0
	v_cndmask_b32_e64 v73, v244, v73, s[22:23]
	v_cmp_ge_i32_e64 s[22:23], v177, v224
	v_add_u32_e32 v224, 50, v223
	v_cmp_ge_i32_e64 s[24:25], v177, v224
	v_add_u32_e32 v224, 19, v223
	s_nop 0
	v_cndmask_b32_e64 v74, v244, v74, s[24:25]
	v_cmp_ge_i32_e64 s[24:25], v177, v224
	v_add_u32_e32 v224, 51, v223
	v_cmp_ge_i32_e64 s[26:27], v177, v224
	v_add_u32_e32 v224, 24, v223
	s_nop 0
	v_cndmask_b32_e64 v75, v244, v75, s[26:27]
	v_cmp_ge_i32_e64 s[26:27], v177, v224
	v_add_u32_e32 v224, 56, v223
	v_cmp_ge_i32_e64 s[28:29], v177, v224
	v_add_u32_e32 v224, 25, v223
	s_nop 0
	v_cndmask_b32_e64 v76, v244, v76, s[28:29]
	v_cmp_ge_i32_e64 s[28:29], v177, v224
	v_add_u32_e32 v224, 57, v223
	v_cmp_ge_i32_e64 s[30:31], v177, v224
	v_add_u32_e32 v224, 26, v223
	s_nop 0
	v_cndmask_b32_e64 v77, v244, v77, s[30:31]
	v_cmp_ge_i32_e64 s[30:31], v177, v224
	v_add_u32_e32 v224, 58, v223
	v_cmp_ge_i32_e64 s[34:35], v177, v224
	v_add_u32_e32 v224, 27, v223
	v_add_u32_e32 v223, 59, v223
	v_cndmask_b32_e64 v78, v244, v78, s[34:35]
	v_cmp_ge_i32_e64 s[34:35], v177, v224
	v_cmp_lt_i32_e64 s[36:37], v177, v223
	s_and_saveexec_b64 s[40:41], s[36:37]
	v_mov_b32_e32 v79, s52
	s_or_b64 exec, exec, s[40:41]
	v_cndmask_b32_e32 v80, v244, v80, vcc
	v_cndmask_b32_e64 v81, v244, v81, s[4:5]
	v_cndmask_b32_e64 v82, v244, v82, s[6:7]
	v_cndmask_b32_e64 v83, v244, v83, s[8:9]
	v_cndmask_b32_e64 v84, v244, v84, s[10:11]
	v_cndmask_b32_e64 v85, v244, v85, s[12:13]
	v_cndmask_b32_e64 v86, v244, v86, s[14:15]
	v_cndmask_b32_e64 v87, v244, v87, s[16:17]
	v_cndmask_b32_e64 v88, v244, v88, s[18:19]
	v_cndmask_b32_e64 v89, v244, v89, s[20:21]
	v_cndmask_b32_e64 v90, v244, v90, s[22:23]
	v_cndmask_b32_e64 v91, v244, v91, s[24:25]
	v_cndmask_b32_e64 v92, v244, v92, s[26:27]
	v_cndmask_b32_e64 v93, v244, v93, s[28:29]
	v_cndmask_b32_e64 v94, v244, v94, s[30:31]
	v_cndmask_b32_e64 v95, v244, v95, s[34:35]
; __device__ __forceinline__ void sm_pv(f32x16& s0, f32x16& s1, f32x16& o0, f32x16& o1, float& m_run, float& l_run, f32x16& negm, LAS unsigned char* vb, bool domask, int kbase, int qm, int r32, int hi) {
;     ...
;     float ma = fmaxf(fmaxf(s0[0], s0[1]), s1[0]), mb = fmaxf(fmaxf(s0[2], s0[3]), s1[1]);
;     ma = fmaxf(fmaxf(ma, s1[2]), s1[3]);
; #pragma unroll
;     for (int r = 4; r < 16; r += 4) { ma = fmaxf(fmaxf(ma, s0[r]), s0[r + 1]); mb = fmaxf(fmaxf(mb, s0[r + 2]), s0[r + 3]); ma = fmaxf(fmaxf(ma, s1[r]), s1[r + 1]); mb = fmaxf(fmaxf(mb, s1[r + 2]), s1[r + 3]); }
;     float mx = fmaxf(ma, mb);
;     { const auto rr = __builtin_amdgcn_permlane32_swap(__float_as_uint(mx), __float_as_uint(mx), false, false); mx = fmaxf(__uint_as_float(rr[0]), __uint_as_float(rr[1])); }
;     if (__builtin_amdgcn_ballot_w64(mx > 8.0f) != 0ull) {
;         const float d = fmaxf(mx, 0.0f);
;         const float alpha = __builtin_amdgcn_exp2f(-d);
;         m_run += d; l_run *= alpha; o0 = o0 * alpha; o1 = o1 * alpha;
;         s0 = s0 - d; s1 = s1 - d;
; #pragma unroll
;         for (int r = 0; r < 16; ++r) negm[r] = -m_run;
;     }
.LBB0_423:
	s_or_b64 exec, exec, s[58:59]
	s_nop 0
	v_max_f32_e32 v223, v80, v81
	v_max3_f32 v224, v82, v83, v65
	v_max3_f32 v223, v223, v64, v66
	v_max3_f32 v223, v223, v67, v84
	v_max3_f32 v224, v224, v86, v87
	v_max3_f32 v223, v223, v85, v68
	v_max3_f32 v224, v224, v70, v71
	v_max3_f32 v223, v223, v69, v88
	v_max3_f32 v224, v224, v90, v91
	v_max3_f32 v223, v223, v89, v72
	v_max3_f32 v224, v224, v74, v75
	v_max3_f32 v223, v223, v73, v92
	v_max3_f32 v224, v224, v94, v95
	v_max3_f32 v223, v223, v93, v76
	v_max3_f32 v224, v224, v78, v79
	v_max3_f32 v223, v223, v77, v224
	v_mov_b32_e32 v224, v223
	s_nop 1
	v_permlane32_swap_b32_e32 v223, v224
	v_max_f32_e32 v223, v223, v224
	v_cmp_lt_f32_e32 vcc, s53, v223
	s_cbranch_vccz .LBB0_425
	v_max_f32_e32 v48, v223, v223
	v_max_f32_e32 v49, 0, v48
	v_exp_f32_e64 v48, -v49
	v_add_f32_e32 v1, v1, v49
	v_sub_f32_e32 v80, v80, v49
	v_sub_f32_e32 v81, v81, v49
	v_mul_f32_e32 v218, v218, v48
	v_pk_mul_f32 v[46:47], v[46:47], v[48:49] op_sel_hi:[1,0]
	v_pk_mul_f32 v[44:45], v[44:45], v[48:49] op_sel_hi:[1,0]
	v_pk_mul_f32 v[42:43], v[42:43], v[48:49] op_sel_hi:[1,0]
	v_pk_mul_f32 v[40:41], v[40:41], v[48:49] op_sel_hi:[1,0]
	v_pk_mul_f32 v[38:39], v[38:39], v[48:49] op_sel_hi:[1,0]
	v_pk_mul_f32 v[36:37], v[36:37], v[48:49] op_sel_hi:[1,0]
	v_pk_mul_f32 v[34:35], v[34:35], v[48:49] op_sel_hi:[1,0]
	v_pk_mul_f32 v[32:33], v[32:33], v[48:49] op_sel_hi:[1,0]
	v_pk_mul_f32 v[30:31], v[30:31], v[48:49] op_sel_hi:[1,0]
	v_pk_mul_f32 v[28:29], v[28:29], v[48:49] op_sel_hi:[1,0]
	v_pk_mul_f32 v[26:27], v[26:27], v[48:49] op_sel_hi:[1,0]
	v_pk_mul_f32 v[24:25], v[24:25], v[48:49] op_sel_hi:[1,0]
	v_pk_mul_f32 v[22:23], v[22:23], v[48:49] op_sel_hi:[1,0]
	v_pk_mul_f32 v[20:21], v[20:21], v[48:49] op_sel_hi:[1,0]
	v_pk_mul_f32 v[18:19], v[18:19], v[48:49] op_sel_hi:[1,0]
	v_pk_mul_f32 v[16:17], v[16:17], v[48:49] op_sel_hi:[1,0]
	v_xor_b32_e32 v48, 0x80000000, v1
	v_sub_f32_e32 v82, v82, v49
	v_sub_f32_e32 v83, v83, v49
	v_sub_f32_e32 v84, v84, v49
	v_sub_f32_e32 v85, v85, v49
	v_sub_f32_e32 v86, v86, v49
	v_sub_f32_e32 v87, v87, v49
	v_sub_f32_e32 v88, v88, v49
	v_sub_f32_e32 v89, v89, v49
	v_sub_f32_e32 v90, v90, v49
	v_sub_f32_e32 v91, v91, v49
	v_sub_f32_e32 v92, v92, v49
	v_sub_f32_e32 v93, v93, v49
	v_sub_f32_e32 v94, v94, v49
	v_sub_f32_e32 v95, v95, v49
	v_sub_f32_e32 v64, v64, v49
	v_sub_f32_e32 v65, v65, v49
	v_sub_f32_e32 v66, v66, v49
	v_sub_f32_e32 v67, v67, v49
	v_sub_f32_e32 v68, v68, v49
	v_sub_f32_e32 v69, v69, v49
	v_sub_f32_e32 v70, v70, v49
	v_sub_f32_e32 v71, v71, v49
	v_sub_f32_e32 v72, v72, v49
	v_sub_f32_e32 v73, v73, v49
	v_sub_f32_e32 v74, v74, v49
	v_sub_f32_e32 v75, v75, v49
	v_sub_f32_e32 v76, v76, v49
	v_sub_f32_e32 v77, v77, v49
	v_sub_f32_e32 v78, v78, v49
	v_sub_f32_e32 v79, v79, v49
	v_mov_b32_e32 v49, v48
	v_mov_b32_e32 v50, v48
	v_mov_b32_e32 v51, v48
	v_mov_b32_e32 v52, v48
	v_mov_b32_e32 v53, v48
	v_mov_b32_e32 v54, v48
	v_mov_b32_e32 v55, v48
	v_mov_b32_e32 v56, v48
	v_mov_b32_e32 v57, v48
	v_mov_b32_e32 v58, v48
	v_mov_b32_e32 v59, v48
	v_mov_b32_e32 v60, v48
	v_mov_b32_e32 v61, v48
	v_mov_b32_e32 v62, v48
	v_mov_b32_e32 v63, v48

; #define LAS __attribute__((address_space(3)))
; __device__ __forceinline__ void qk_tile(f32x16& s0, f32x16& s1, LAS unsigned char* kb, const bf16x8 (&qr)[6], const f32x16& negm, int r32, int hi) {
;     bf16x8 kf[12];
; #pragma unroll
;     for (int ks = 0; ks < 6; ++ks) { kf[2 * ks] = *(const LAS bf16x8*)(kb + r32 * KPT + ks * 32 + hi * 16); kf[2 * ks + 1] = *(const LAS bf16x8*)(kb + (32 + r32) * KPT + ks * 32 + hi * 16); }
;     __builtin_amdgcn_sched_barrier(0);
; #pragma unroll
;     for (int ks = 0; ks < 6; ++ks) {
;         s0 = __builtin_amdgcn_mfma_f32_32x32x16_bf16(kf[2 * ks], qr[ks], ks == 0 ? negm : s0, 0, 0, 0);
;         s1 = __builtin_amdgcn_mfma_f32_32x32x16_bf16(kf[2 * ks + 1], qr[ks], ks == 0 ? negm : s1, 0, 0, 0);
;     }
; }
.LBB0_426:
	s_or_b64 exec, exec, s[46:47]
	ds_write_b128 v210, v[120:123]
	s_and_saveexec_b64 s[4:5], s[2:3]
	ds_write_b128 v210, v[124:127] offset:128
	s_or_b64 exec, exec, s[4:5]
	s_waitcnt vmcnt(4)
	v_perm_b32 v10, v186, v184, s94
	v_perm_b32 v11, v186, v184, s95
	ds_write2_b32 v214, v10, v11 offset1:34
	v_perm_b32 v10, v187, v185, s94
	v_perm_b32 v11, v187, v185, s95
	ds_write2_b32 v214, v10, v11 offset0:68 offset1:102
	s_waitcnt lgkmcnt(0)
	s_barrier
	s_andn2_b64 vcc, exec, s[44:45]
	s_cbranch_vccnz .LBB0_417
	s_cmp_gt_u32 s84, s57
	s_cselect_b32 s4, s79, 0
	s_lshl_b32 s4, s4, 6
	s_sub_i32 s5, 0xc0, s4
	v_add_u32_e32 v120, s5, v221
	v_add_u32_e32 v184, s5, v222
	s_add_i32 s4, s83, 64
	v_cmp_le_u32_e32 vcc, s4, v220
	s_and_saveexec_b64 s[44:45], vcc
	s_cbranch_execz .Latt_sk2
	ds_read_b128 v[10:13], v241
	ds_read_b128 v[136:139], v241 offset:32
	ds_read_b128 v[140:143], v241 offset:6656
	ds_read_b128 v[144:147], v241 offset:6688
	ds_read_b128 v[148:151], v241 offset:64
	ds_read_b128 v[152:155], v241 offset:96
	ds_read_b128 v[156:159], v241 offset:6720
	ds_read_b128 v[160:163], v241 offset:6752
	ds_read_b128 v[222:225], v241 offset:128
	ds_read_b128 v[226:229], v241 offset:160
	ds_read_b128 v[230:233], v241 offset:6784
	ds_read_b128 v[234:237], v241 offset:6816
	s_waitcnt lgkmcnt(11)
	v_mfma_f32_32x32x16_bf16 v[80:95], v[10:13], v[96:99], v[48:63]
	s_add_i32 s4, s83, 0x7f
	v_cmp_gt_i32_e32 vcc, s4, v175
	s_waitcnt lgkmcnt(9)
	v_mfma_f32_32x32x16_bf16 v[64:79], v[140:143], v[96:99], v[48:63]
	v_mfma_f32_32x32x16_bf16 v[80:95], v[136:139], v[100:103], v[80:95]
	s_waitcnt lgkmcnt(8)
	v_mfma_f32_32x32x16_bf16 v[64:79], v[144:147], v[100:103], v[64:79]
	s_waitcnt lgkmcnt(7)
	v_mfma_f32_32x32x16_bf16 v[80:95], v[148:151], v[104:107], v[80:95]
	s_waitcnt lgkmcnt(5)
	v_mfma_f32_32x32x16_bf16 v[64:79], v[156:159], v[104:107], v[64:79]
	v_mfma_f32_32x32x16_bf16 v[80:95], v[152:155], v[108:111], v[80:95]
	ds_read2_b64 v[152:155], v252 offset0:4 offset1:6
	s_waitcnt lgkmcnt(5)
	v_mfma_f32_32x32x16_bf16 v[64:79], v[160:163], v[108:111], v[64:79]
	ds_read2_b64 v[160:163], v252 offset1:2
	ds_read2_b64 v[156:159], v253 offset0:32 offset1:34
	ds_read2_b64 v[148:151], v253 offset0:36 offset1:38
	ds_read2_b64 v[144:147], v252 offset0:8 offset1:10
	ds_read2_b64 v[140:143], v253 offset0:40 offset1:42
	ds_read2_b64 v[136:139], v252 offset0:12 offset1:14
	ds_read2_b64 v[10:13], v253 offset0:44 offset1:46
	s_waitcnt lgkmcnt(11)
	v_mfma_f32_32x32x16_bf16 v[80:95], v[222:225], v[112:115], v[80:95]
	s_waitcnt lgkmcnt(9)
	v_mfma_f32_32x32x16_bf16 v[64:79], v[230:233], v[112:115], v[64:79]
	v_mfma_f32_32x32x16_bf16 v[80:95], v[226:229], v[116:119], v[80:95]
	s_waitcnt lgkmcnt(8)
	v_mfma_f32_32x32x16_bf16 v[64:79], v[234:237], v[116:119], v[64:79]
	v_min_u32_e32 v120, 0x80ff, v120
	v_add_u32_e32 v186, 1, v184
	v_min_u32_e32 v184, 0x80ff, v184
	v_min_u32_e32 v186, 0x80ff, v186
	v_lshl_add_u32 v122, v120, 12, v238
	v_lshl_add_u32 v124, v120, 6, v239
	v_lshl_add_u32 v184, v184, 12, v174
	v_lshl_add_u32 v186, v186, 12, v174
	global_load_dwordx4 v[120:123], v122, s[98:99]
	s_nop 0
	global_load_dwordx4 v[124:127], v124, s[100:101]
	global_load_dwordx2 v[184:185], v184, s[98:99] offset:128
	global_load_dwordx2 v[186:187], v186, s[98:99] offset:128
	s_and_saveexec_b64 s[46:47], vcc
	s_cbranch_execz .LBB0_434
; __device__ __forceinline__ void sm_pv(f32x16& s0, f32x16& s1, f32x16& o0, f32x16& o1, float& m_run, float& l_run, f32x16& negm, LAS unsigned char* vb, bool domask, int kbase, int qm, int r32, int hi) {
;     ...
;     if (domask) {
;         const int kb0 = kbase + 4 * hi;
; #pragma unroll
;         for (int r = 0; r < 16; ++r) { const int kv = kb0 + (r & 3) + 8 * (r >> 2); if (kv > qm) s0[r] = -INFINITY; if (kv + 32 > qm) s1[r] = -INFINITY; }
;     }
;     float ma = fmaxf(fmaxf(s0[0], s0[1]), s1[0]), mb = fmaxf(fmaxf(s0[2], s0[3]), s1[1]);
;     ma = fmaxf(fmaxf(ma, s1[2]), s1[3]);
; #pragma unroll
;     for (int r = 4; r < 16; r += 4) { ma = fmaxf(fmaxf(ma, s0[r]), s0[r + 1]); mb = fmaxf(fmaxf(mb, s0[r + 2]), s0[r + 3]); ma = fmaxf(fmaxf(ma, s1[r]), s1[r + 1]); mb = fmaxf(fmaxf(mb, s1[r + 2]), s1[r + 3]); }
;     float mx = fmaxf(ma, mb);
;     { const auto rr = __builtin_amdgcn_permlane32_swap(__float_as_uint(mx), __float_as_uint(mx), false, false); mx = fmaxf(__uint_as_float(rr[0]), __uint_as_float(rr[1])); }
;     if (__builtin_amdgcn_ballot_w64(mx > 8.0f) != 0ull) {
;         const float d = fmaxf(mx, 0.0f);
;         const float alpha = __builtin_amdgcn_exp2f(-d);
;         m_run += d; l_run *= alpha; o0 = o0 * alpha; o1 = o1 * alpha;
;         s0 = s0 - d; s1 = s1 - d;
; #pragma unroll
;         for (int r = 0; r < 16; ++r) negm[r] = -m_run;
;     }
	v_add_u32_e32 v221, s83, v201
	v_add_u32_e32 v223, 0x60, v221
	v_add_u32_e32 v222, 64, v221
	v_cmp_le_u32_e64 s[4:5], v223, v219
	v_cmp_le_u32_e32 vcc, v222, v219
	s_nop 4
	v_cndmask_b32_e64 v64, v244, v64, s[4:5]
	v_cmp_lt_u32_e64 s[4:5], v222, v219
	v_add_u32_e32 v222, 0x61, v221
	v_cmp_le_u32_e64 s[6:7], v222, v219
	v_add_u32_e32 v222, 0x42, v221
	s_nop 0
	v_cndmask_b32_e64 v65, v244, v65, s[6:7]
	v_cmp_le_u32_e64 s[6:7], v222, v219
	v_add_u32_e32 v222, 0x62, v221
	v_cmp_le_u32_e64 s[8:9], v222, v219
	v_add_u32_e32 v222, 0x43, v221
	s_nop 0
	v_cndmask_b32_e64 v66, v244, v66, s[8:9]
	v_cmp_le_u32_e64 s[8:9], v222, v219
	v_add_u32_e32 v222, 0x63, v221
	v_cmp_le_u32_e64 s[10:11], v222, v219
	v_add_u32_e32 v222, 0x48, v221
	s_nop 0
	v_cndmask_b32_e64 v67, v244, v67, s[10:11]
	v_cmp_le_u32_e64 s[10:11], v222, v219
	v_add_u32_e32 v222, 0x68, v221
	v_cmp_le_u32_e64 s[12:13], v222, v219
	v_add_u32_e32 v222, 0x49, v221
	s_nop 0
	v_cndmask_b32_e64 v68, v244, v68, s[12:13]
	v_cmp_le_u32_e64 s[12:13], v222, v219
	v_add_u32_e32 v222, 0x69, v221
	v_cmp_le_u32_e64 s[14:15], v222, v219
	v_add_u32_e32 v222, 0x4a, v221
	s_nop 0
	v_cndmask_b32_e64 v69, v244, v69, s[14:15]
	v_cmp_le_u32_e64 s[14:15], v222, v219
	v_add_u32_e32 v222, 0x6a, v221
	v_cmp_le_u32_e64 s[16:17], v222, v219
	v_add_u32_e32 v222, 0x4b, v221
	s_nop 0
	v_cndmask_b32_e64 v70, v244, v70, s[16:17]
	v_cmp_le_u32_e64 s[16:17], v222, v219
	v_add_u32_e32 v222, 0x6b, v221
	v_cmp_le_u32_e64 s[18:19], v222, v219
	v_add_u32_e32 v222, 0x50, v221
	s_nop 0
	v_cndmask_b32_e64 v71, v244, v71, s[18:19]
	v_cmp_le_u32_e64 s[18:19], v222, v219
	v_add_u32_e32 v222, 0x70, v221
	v_cmp_le_u32_e64 s[20:21], v222, v219
	v_add_u32_e32 v222, 0x51, v221
	s_nop 0
	v_cndmask_b32_e64 v72, v244, v72, s[20:21]
	v_cmp_le_u32_e64 s[20:21], v222, v219
	v_add_u32_e32 v222, 0x71, v221
	v_cmp_le_u32_e64 s[22:23], v222, v219
	v_add_u32_e32 v222, 0x52, v221
	s_nop 0
	v_cndmask_b32_e64 v73, v244, v73, s[22:23]
	v_cmp_le_u32_e64 s[22:23], v222, v219
	v_add_u32_e32 v222, 0x72, v221
	v_cmp_le_u32_e64 s[24:25], v222, v219
	v_add_u32_e32 v222, 0x53, v221
	s_nop 0
	v_cndmask_b32_e64 v74, v244, v74, s[24:25]
	v_cmp_le_u32_e64 s[24:25], v222, v219
	v_add_u32_e32 v222, 0x73, v221
	v_cmp_le_u32_e64 s[26:27], v222, v219
	v_add_u32_e32 v222, 0x58, v221
	s_nop 0
	v_cndmask_b32_e64 v75, v244, v75, s[26:27]
	v_cmp_le_u32_e64 s[26:27], v222, v219
	v_add_u32_e32 v222, 0x78, v221
	v_cmp_le_u32_e64 s[28:29], v222, v219
	v_add_u32_e32 v222, 0x59, v221
	s_nop 0
	v_cndmask_b32_e64 v76, v244, v76, s[28:29]
	v_cmp_le_u32_e64 s[28:29], v222, v219
	v_add_u32_e32 v222, 0x79, v221
	v_cmp_le_u32_e64 s[30:31], v222, v219
	v_add_u32_e32 v222, 0x5a, v221
	s_nop 0
	v_cndmask_b32_e64 v77, v244, v77, s[30:31]
	v_cmp_le_u32_e64 s[30:31], v222, v219
	v_add_u32_e32 v222, 0x7a, v221
	v_cmp_le_u32_e64 s[34:35], v222, v219
	v_add_u32_e32 v222, 0x5b, v221
	v_add_u32_e32 v221, 0x7b, v221
	v_cndmask_b32_e64 v78, v244, v78, s[34:35]
	v_cmp_le_u32_e64 s[34:35], v222, v219
	v_cmp_gt_u32_e64 s[36:37], v221, v219
	s_and_saveexec_b64 s[40:41], s[36:37]
	v_mov_b32_e32 v79, s52
	s_or_b64 exec, exec, s[40:41]
	v_cndmask_b32_e64 v81, v244, v81, s[4:5]
	v_cndmask_b32_e32 v80, v244, v80, vcc
	v_cndmask_b32_e64 v82, v244, v82, s[6:7]
	v_cndmask_b32_e64 v83, v244, v83, s[8:9]
	v_cndmask_b32_e64 v84, v244, v84, s[10:11]
	v_cndmask_b32_e64 v85, v244, v85, s[12:13]
	v_cndmask_b32_e64 v86, v244, v86, s[14:15]
	v_cndmask_b32_e64 v87, v244, v87, s[16:17]
	v_cndmask_b32_e64 v88, v244, v88, s[18:19]
	v_cndmask_b32_e64 v89, v244, v89, s[20:21]
	v_cndmask_b32_e64 v90, v244, v90, s[22:23]
	v_cndmask_b32_e64 v91, v244, v91, s[24:25]
	v_cndmask_b32_e64 v92, v244, v92, s[26:27]
	v_cndmask_b32_e64 v93, v244, v93, s[28:29]
	v_cndmask_b32_e64 v94, v244, v94, s[30:31]
	v_cndmask_b32_e64 v95, v244, v95, s[34:35]
.LBB0_434:
	s_or_b64 exec, exec, s[46:47]
	s_nop 0
	v_max_f32_e32 v221, v80, v81
	v_max3_f32 v222, v82, v83, v65
	v_max3_f32 v221, v221, v64, v66
	v_max3_f32 v221, v221, v67, v84
	v_max3_f32 v222, v222, v86, v87
	v_max3_f32 v221, v221, v85, v68
	v_max3_f32 v222, v222, v70, v71
	v_max3_f32 v221, v221, v69, v88
	v_max3_f32 v222, v222, v90, v91
	v_max3_f32 v221, v221, v89, v72
	v_max3_f32 v222, v222, v74, v75
	v_max3_f32 v221, v221, v73, v92
	v_max3_f32 v222, v222, v94, v95
	v_max3_f32 v221, v221, v93, v76
	v_max3_f32 v222, v222, v78, v79
	v_max3_f32 v221, v221, v77, v222
	v_mov_b32_e32 v222, v221
	s_nop 1
	v_permlane32_swap_b32_e32 v221, v222
	v_max_f32_e32 v221, v221, v222
	v_cmp_lt_f32_e32 vcc, s53, v221
	s_cbranch_vccz .LBB0_436
	v_max_f32_e32 v48, v221, v221
	v_max_f32_e32 v49, 0, v48
	v_exp_f32_e64 v48, -v49
	v_add_f32_e32 v1, v1, v49
	v_sub_f32_e32 v80, v80, v49
	v_sub_f32_e32 v81, v81, v49
	v_mul_f32_e32 v218, v218, v48
	v_pk_mul_f32 v[46:47], v[46:47], v[48:49] op_sel_hi:[1,0]
	v_pk_mul_f32 v[44:45], v[44:45], v[48:49] op_sel_hi:[1,0]
	v_pk_mul_f32 v[42:43], v[42:43], v[48:49] op_sel_hi:[1,0]
	v_pk_mul_f32 v[40:41], v[40:41], v[48:49] op_sel_hi:[1,0]
	v_pk_mul_f32 v[38:39], v[38:39], v[48:49] op_sel_hi:[1,0]
	v_pk_mul_f32 v[36:37], v[36:37], v[48:49] op_sel_hi:[1,0]
	v_pk_mul_f32 v[34:35], v[34:35], v[48:49] op_sel_hi:[1,0]
	v_pk_mul_f32 v[32:33], v[32:33], v[48:49] op_sel_hi:[1,0]
	v_pk_mul_f32 v[30:31], v[30:31], v[48:49] op_sel_hi:[1,0]
	v_pk_mul_f32 v[28:29], v[28:29], v[48:49] op_sel_hi:[1,0]
	v_pk_mul_f32 v[26:27], v[26:27], v[48:49] op_sel_hi:[1,0]
	v_pk_mul_f32 v[24:25], v[24:25], v[48:49] op_sel_hi:[1,0]
	v_pk_mul_f32 v[22:23], v[22:23], v[48:49] op_sel_hi:[1,0]
	v_pk_mul_f32 v[20:21], v[20:21], v[48:49] op_sel_hi:[1,0]
	v_pk_mul_f32 v[18:19], v[18:19], v[48:49] op_sel_hi:[1,0]
	v_pk_mul_f32 v[16:17], v[16:17], v[48:49] op_sel_hi:[1,0]
	v_xor_b32_e32 v48, 0x80000000, v1
	v_sub_f32_e32 v82, v82, v49
	v_sub_f32_e32 v83, v83, v49
	v_sub_f32_e32 v84, v84, v49
	v_sub_f32_e32 v85, v85, v49
	v_sub_f32_e32 v86, v86, v49
	v_sub_f32_e32 v87, v87, v49
	v_sub_f32_e32 v88, v88, v49
	v_sub_f32_e32 v89, v89, v49
	v_sub_f32_e32 v90, v90, v49
	v_sub_f32_e32 v91, v91, v49
	v_sub_f32_e32 v92, v92, v49
	v_sub_f32_e32 v93, v93, v49
	v_sub_f32_e32 v94, v94, v49
	v_sub_f32_e32 v95, v95, v49
	v_sub_f32_e32 v64, v64, v49
	v_sub_f32_e32 v65, v65, v49
	v_sub_f32_e32 v66, v66, v49
	v_sub_f32_e32 v67, v67, v49
	v_sub_f32_e32 v68, v68, v49
	v_sub_f32_e32 v69, v69, v49
	v_sub_f32_e32 v70, v70, v49
	v_sub_f32_e32 v71, v71, v49
	v_sub_f32_e32 v72, v72, v49
	v_sub_f32_e32 v73, v73, v49
	v_sub_f32_e32 v74, v74, v49
	v_sub_f32_e32 v75, v75, v49
	v_sub_f32_e32 v76, v76, v49
	v_sub_f32_e32 v77, v77, v49
	v_sub_f32_e32 v78, v78, v49
	v_sub_f32_e32 v79, v79, v49
	v_mov_b32_e32 v49, v48
	v_mov_b32_e32 v50, v48
	v_mov_b32_e32 v51, v48
	v_mov_b32_e32 v52, v48
	v_mov_b32_e32 v53, v48
	v_mov_b32_e32 v54, v48
	v_mov_b32_e32 v55, v48
	v_mov_b32_e32 v56, v48
	v_mov_b32_e32 v57, v48
	v_mov_b32_e32 v58, v48
	v_mov_b32_e32 v59, v48
	v_mov_b32_e32 v60, v48
	v_mov_b32_e32 v61, v48
	v_mov_b32_e32 v62, v48
	v_mov_b32_e32 v63, v48

; #define LAS __attribute__((address_space(3)))
; __device__ __forceinline__ void qk_tile(f32x16& s0, f32x16& s1, LAS unsigned char* kb, const bf16x8 (&qr)[6], const f32x16& negm, int r32, int hi) {
;     bf16x8 kf[12];
; #pragma unroll
;     for (int ks = 0; ks < 6; ++ks) { kf[2 * ks] = *(const LAS bf16x8*)(kb + r32 * KPT + ks * 32 + hi * 16); kf[2 * ks + 1] = *(const LAS bf16x8*)(kb + (32 + r32) * KPT + ks * 32 + hi * 16); }
;     __builtin_amdgcn_sched_barrier(0);
; #pragma unroll
;     for (int ks = 0; ks < 6; ++ks) {
;         s0 = __builtin_amdgcn_mfma_f32_32x32x16_bf16(kf[2 * ks], qr[ks], ks == 0 ? negm : s0, 0, 0, 0);
;         s1 = __builtin_amdgcn_mfma_f32_32x32x16_bf16(kf[2 * ks + 1], qr[ks], ks == 0 ? negm : s1, 0, 0, 0);
;     }
; }
; __device__ __forceinline__ void sm_pv(f32x16& s0, f32x16& s1, f32x16& o0, f32x16& o1, float& m_run, float& l_run, f32x16& negm, LAS unsigned char* vb, bool domask, int kbase, int qm, int r32, int hi) {
;     s16x4 vlo[8], vhh[8];
; #pragma unroll
;     for (int kk = 0; kk < 4; ++kk) { const int koff = 2 * (16 * kk + 4 * hi);
;         vlo[2 * kk] = *(const LAS s16x4*)(vb + r32 * VP + koff); vhh[2 * kk] = *(const LAS s16x4*)(vb + r32 * VP + koff + 16);
;         vlo[2 * kk + 1] = *(const LAS s16x4*)(vb + (32 + r32) * VP + koff); vhh[2 * kk + 1] = *(const LAS s16x4*)(vb + (32 + r32) * VP + koff + 16); }
;     __builtin_amdgcn_sched_barrier(0);
;     if (domask) {
;         const int kb0 = kbase + 4 * hi;
; #pragma unroll
;         for (int r = 0; r < 16; ++r) { const int kv = kb0 + (r & 3) + 8 * (r >> 2); if (kv > qm) s0[r] = -INFINITY; if (kv + 32 > qm) s1[r] = -INFINITY; }
;     }
.LBB0_443:
	s_add_i32 s85, s84, -3
	s_cmp_lt_u32 s85, s57
	s_cselect_b64 s[44:45], -1, 0
	s_and_b64 s[4:5], s[44:45], exec
	s_cselect_b32 s4, 0, s79
	s_lshl_b32 s4, s4, 6
	s_sub_i32 s5, 0x80, s4
	v_add_u32_e32 v14, s83, v213
	v_add_u32_e32 v15, s83, v173
	v_cmp_le_u32_e32 vcc, s83, v220
	s_and_saveexec_b64 s[46:47], vcc
	s_cbranch_execz .Latt_sk3
	ds_read_b128 v[2:5], v241
	ds_read_b128 v[6:9], v241 offset:32
	ds_read_b128 v[10:13], v241 offset:6656
	ds_read_b128 v[136:139], v241 offset:6688
	ds_read_b128 v[140:143], v241 offset:64
	ds_read_b128 v[144:147], v241 offset:96
	ds_read_b128 v[148:151], v241 offset:6720
	ds_read_b128 v[152:155], v241 offset:6752
	ds_read_b128 v[156:159], v241 offset:128
	ds_read_b128 v[160:163], v241 offset:160
	ds_read_b128 v[222:225], v241 offset:6784
	ds_read_b128 v[226:229], v241 offset:6816
	s_waitcnt lgkmcnt(11)
	v_mfma_f32_32x32x16_bf16 v[80:95], v[2:5], v[96:99], v[48:63]
	s_add_i32 s4, s83, 63
	v_cmp_gt_i32_e32 vcc, s4, v175
	s_waitcnt lgkmcnt(9)
	v_mfma_f32_32x32x16_bf16 v[64:79], v[10:13], v[96:99], v[48:63]
	v_mfma_f32_32x32x16_bf16 v[80:95], v[6:9], v[100:103], v[80:95]
	s_waitcnt lgkmcnt(8)
	v_mfma_f32_32x32x16_bf16 v[64:79], v[136:139], v[100:103], v[64:79]
	s_waitcnt lgkmcnt(7)
	v_mfma_f32_32x32x16_bf16 v[80:95], v[140:143], v[104:107], v[80:95]
	s_waitcnt lgkmcnt(5)
	v_mfma_f32_32x32x16_bf16 v[64:79], v[148:151], v[104:107], v[64:79]
	v_mfma_f32_32x32x16_bf16 v[80:95], v[144:147], v[108:111], v[80:95]
	ds_read2_b64 v[144:147], v252 offset0:4 offset1:6
	s_waitcnt lgkmcnt(5)
	v_mfma_f32_32x32x16_bf16 v[64:79], v[152:155], v[108:111], v[64:79]
	ds_read2_b64 v[152:155], v252 offset1:2
	ds_read2_b64 v[148:151], v253 offset0:32 offset1:34
	ds_read2_b64 v[140:143], v253 offset0:36 offset1:38
	ds_read2_b64 v[136:139], v252 offset0:8 offset1:10
	ds_read2_b64 v[10:13], v253 offset0:40 offset1:42
	ds_read2_b64 v[6:9], v252 offset0:12 offset1:14
	ds_read2_b64 v[2:5], v253 offset0:44 offset1:46
	s_waitcnt lgkmcnt(11)
	v_mfma_f32_32x32x16_bf16 v[80:95], v[156:159], v[112:115], v[80:95]
	s_waitcnt lgkmcnt(9)
	v_mfma_f32_32x32x16_bf16 v[64:79], v[222:225], v[112:115], v[64:79]
	v_mfma_f32_32x32x16_bf16 v[80:95], v[160:163], v[116:119], v[80:95]
	s_waitcnt lgkmcnt(8)
	v_mfma_f32_32x32x16_bf16 v[64:79], v[226:229], v[116:119], v[64:79]
	v_add_u32_e32 v120, s5, v14
	v_add_u32_e32 v184, s5, v15
	v_min_u32_e32 v120, 0x80ff, v120
	v_add_u32_e32 v186, 1, v184
	v_min_u32_e32 v184, 0x80ff, v184
	v_min_u32_e32 v186, 0x80ff, v186
	v_lshl_add_u32 v122, v120, 12, v238
	v_lshl_add_u32 v124, v120, 6, v239
	v_lshl_add_u32 v184, v184, 12, v174
	v_lshl_add_u32 v186, v186, 12, v174
	global_load_dwordx4 v[120:123], v122, s[98:99]
	s_nop 0
	global_load_dwordx4 v[124:127], v124, s[100:101]
	global_load_dwordx2 v[184:185], v184, s[98:99] offset:128
	global_load_dwordx2 v[186:187], v186, s[98:99] offset:128
	s_and_saveexec_b64 s[58:59], vcc
	s_cbranch_execz .LBB0_448
	v_add_u32_e32 v156, s83, v201
	v_add_u32_e32 v157, 32, v156
	v_cmp_ge_i32_e64 s[4:5], v177, v157
	v_add_u32_e32 v157, 33, v156
	v_cmp_ge_i32_e64 s[6:7], v177, v157
	v_add_u32_e32 v157, 2, v156
	v_cmp_le_u32_e32 vcc, v156, v219
	s_nop 2
	v_cndmask_b32_e64 v65, v244, v65, s[6:7]
	v_cmp_ge_i32_e64 s[6:7], v177, v157
	v_add_u32_e32 v157, 34, v156
	v_cmp_ge_i32_e64 s[8:9], v177, v157
	v_add_u32_e32 v157, 3, v156
	v_cndmask_b32_e64 v64, v244, v64, s[4:5]
	v_cndmask_b32_e64 v66, v244, v66, s[8:9]
	v_cmp_ge_i32_e64 s[8:9], v177, v157
	v_add_u32_e32 v157, 35, v156
	v_cmp_ge_i32_e64 s[10:11], v177, v157
	v_add_u32_e32 v157, 8, v156
	v_cmp_gt_i32_e64 s[4:5], v177, v156
	v_cndmask_b32_e64 v67, v244, v67, s[10:11]
	v_cmp_ge_i32_e64 s[10:11], v177, v157
	v_add_u32_e32 v157, 40, v156
	v_cmp_ge_i32_e64 s[12:13], v177, v157
	v_add_u32_e32 v157, 9, v156
	s_nop 0
	v_cndmask_b32_e64 v68, v244, v68, s[12:13]
	v_cmp_ge_i32_e64 s[12:13], v177, v157
	v_add_u32_e32 v157, 41, v156
	v_cmp_ge_i32_e64 s[14:15], v177, v157
	v_add_u32_e32 v157, 10, v156
	s_nop 0
	v_cndmask_b32_e64 v69, v244, v69, s[14:15]
	v_cmp_ge_i32_e64 s[14:15], v177, v157
	v_add_u32_e32 v157, 42, v156
	v_cmp_ge_i32_e64 s[16:17], v177, v157
	v_add_u32_e32 v157, 11, v156
	s_nop 0
	v_cndmask_b32_e64 v70, v244, v70, s[16:17]
	v_cmp_ge_i32_e64 s[16:17], v177, v157
	v_add_u32_e32 v157, 43, v156
	v_cmp_ge_i32_e64 s[18:19], v177, v157
	v_add_u32_e32 v157, 16, v156
	s_nop 0
	v_cndmask_b32_e64 v71, v244, v71, s[18:19]
	v_cmp_ge_i32_e64 s[18:19], v177, v157
	v_add_u32_e32 v157, 48, v156
	v_cmp_ge_i32_e64 s[20:21], v177, v157
	v_add_u32_e32 v157, 17, v156
	s_nop 0
	v_cndmask_b32_e64 v72, v244, v72, s[20:21]
	v_cmp_ge_i32_e64 s[20:21], v177, v157
	v_add_u32_e32 v157, 49, v156
	v_cmp_ge_i32_e64 s[22:23], v177, v157
	v_add_u32_e32 v157, 18, v156
	s_nop 0
	v_cndmask_b32_e64 v73, v244, v73, s[22:23]
	v_cmp_ge_i32_e64 s[22:23], v177, v157
	v_add_u32_e32 v157, 50, v156
	v_cmp_ge_i32_e64 s[24:25], v177, v157
	v_add_u32_e32 v157, 19, v156
	s_nop 0
	v_cndmask_b32_e64 v74, v244, v74, s[24:25]
	v_cmp_ge_i32_e64 s[24:25], v177, v157
	v_add_u32_e32 v157, 51, v156
	v_cmp_ge_i32_e64 s[26:27], v177, v157
	v_add_u32_e32 v157, 24, v156
	s_nop 0
	v_cndmask_b32_e64 v75, v244, v75, s[26:27]
	v_cmp_ge_i32_e64 s[26:27], v177, v157
	v_add_u32_e32 v157, 56, v156
	v_cmp_ge_i32_e64 s[28:29], v177, v157
	v_add_u32_e32 v157, 25, v156
	s_nop 0
	v_cndmask_b32_e64 v76, v244, v76, s[28:29]
	v_cmp_ge_i32_e64 s[28:29], v177, v157
	v_add_u32_e32 v157, 57, v156
	v_cmp_ge_i32_e64 s[30:31], v177, v157
	v_add_u32_e32 v157, 26, v156
	s_nop 0
	v_cndmask_b32_e64 v77, v244, v77, s[30:31]
	v_cmp_ge_i32_e64 s[30:31], v177, v157
	v_add_u32_e32 v157, 58, v156
	v_cmp_ge_i32_e64 s[34:35], v177, v157
	v_add_u32_e32 v157, 27, v156
	v_add_u32_e32 v156, 59, v156
	v_cndmask_b32_e64 v78, v244, v78, s[34:35]
	v_cmp_ge_i32_e64 s[34:35], v177, v157
	v_cmp_lt_i32_e64 s[36:37], v177, v156
	s_and_saveexec_b64 s[40:41], s[36:37]
	v_mov_b32_e32 v79, s52
	s_or_b64 exec, exec, s[40:41]
	v_cndmask_b32_e32 v80, v244, v80, vcc
	v_cndmask_b32_e64 v81, v244, v81, s[4:5]
	v_cndmask_b32_e64 v82, v244, v82, s[6:7]
	v_cndmask_b32_e64 v83, v244, v83, s[8:9]
	v_cndmask_b32_e64 v84, v244, v84, s[10:11]
	v_cndmask_b32_e64 v85, v244, v85, s[12:13]
	v_cndmask_b32_e64 v86, v244, v86, s[14:15]
	v_cndmask_b32_e64 v87, v244, v87, s[16:17]
	v_cndmask_b32_e64 v88, v244, v88, s[18:19]
	v_cndmask_b32_e64 v89, v244, v89, s[20:21]
	v_cndmask_b32_e64 v90, v244, v90, s[22:23]
	v_cndmask_b32_e64 v91, v244, v91, s[24:25]
	v_cndmask_b32_e64 v92, v244, v92, s[26:27]
	v_cndmask_b32_e64 v93, v244, v93, s[28:29]
	v_cndmask_b32_e64 v94, v244, v94, s[30:31]
	v_cndmask_b32_e64 v95, v244, v95, s[34:35]
; __device__ __forceinline__ void sm_pv(f32x16& s0, f32x16& s1, f32x16& o0, f32x16& o1, float& m_run, float& l_run, f32x16& negm, LAS unsigned char* vb, bool domask, int kbase, int qm, int r32, int hi) {
;     ...
;     float ma = fmaxf(fmaxf(s0[0], s0[1]), s1[0]), mb = fmaxf(fmaxf(s0[2], s0[3]), s1[1]);
;     ma = fmaxf(fmaxf(ma, s1[2]), s1[3]);
; #pragma unroll
;     for (int r = 4; r < 16; r += 4) { ma = fmaxf(fmaxf(ma, s0[r]), s0[r + 1]); mb = fmaxf(fmaxf(mb, s0[r + 2]), s0[r + 3]); ma = fmaxf(fmaxf(ma, s1[r]), s1[r + 1]); mb = fmaxf(fmaxf(mb, s1[r + 2]), s1[r + 3]); }
;     float mx = fmaxf(ma, mb);
;     { const auto rr = __builtin_amdgcn_permlane32_swap(__float_as_uint(mx), __float_as_uint(mx), false, false); mx = fmaxf(__uint_as_float(rr[0]), __uint_as_float(rr[1])); }
;     if (__builtin_amdgcn_ballot_w64(mx > 8.0f) != 0ull) {
;         const float d = fmaxf(mx, 0.0f);
;         const float alpha = __builtin_amdgcn_exp2f(-d);
;         m_run += d; l_run *= alpha; o0 = o0 * alpha; o1 = o1 * alpha;
;         s0 = s0 - d; s1 = s1 - d;
; #pragma unroll
;         for (int r = 0; r < 16; ++r) negm[r] = -m_run;
;     }
.LBB0_448:
	s_or_b64 exec, exec, s[58:59]
	s_nop 0
	v_max_f32_e32 v156, v80, v81
	v_max3_f32 v157, v82, v83, v65
	v_max3_f32 v156, v156, v64, v66
	v_max3_f32 v156, v156, v67, v84
	v_max3_f32 v157, v157, v86, v87
	v_max3_f32 v156, v156, v85, v68
	v_max3_f32 v157, v157, v70, v71
	v_max3_f32 v156, v156, v69, v88
	v_max3_f32 v157, v157, v90, v91
	v_max3_f32 v156, v156, v89, v72
	v_max3_f32 v157, v157, v74, v75
	v_max3_f32 v156, v156, v73, v92
	v_max3_f32 v157, v157, v94, v95
	v_max3_f32 v156, v156, v93, v76
	v_max3_f32 v157, v157, v78, v79
	v_max3_f32 v156, v156, v77, v157
	v_mov_b32_e32 v157, v156
	s_nop 1
	v_permlane32_swap_b32_e32 v156, v157
	v_max_f32_e32 v156, v156, v157
	v_cmp_lt_f32_e32 vcc, s53, v156
	s_cbranch_vccz .LBB0_450
	v_max_f32_e32 v48, v156, v156
	v_max_f32_e32 v49, 0, v48
	v_exp_f32_e64 v48, -v49
	v_add_f32_e32 v1, v1, v49
	v_sub_f32_e32 v80, v80, v49
	v_sub_f32_e32 v81, v81, v49
	v_mul_f32_e32 v218, v218, v48
	v_pk_mul_f32 v[46:47], v[46:47], v[48:49] op_sel_hi:[1,0]
	v_pk_mul_f32 v[44:45], v[44:45], v[48:49] op_sel_hi:[1,0]
	v_pk_mul_f32 v[42:43], v[42:43], v[48:49] op_sel_hi:[1,0]
	v_pk_mul_f32 v[40:41], v[40:41], v[48:49] op_sel_hi:[1,0]
	v_pk_mul_f32 v[38:39], v[38:39], v[48:49] op_sel_hi:[1,0]
	v_pk_mul_f32 v[36:37], v[36:37], v[48:49] op_sel_hi:[1,0]
	v_pk_mul_f32 v[34:35], v[34:35], v[48:49] op_sel_hi:[1,0]
	v_pk_mul_f32 v[32:33], v[32:33], v[48:49] op_sel_hi:[1,0]
	v_pk_mul_f32 v[30:31], v[30:31], v[48:49] op_sel_hi:[1,0]
	v_pk_mul_f32 v[28:29], v[28:29], v[48:49] op_sel_hi:[1,0]
	v_pk_mul_f32 v[26:27], v[26:27], v[48:49] op_sel_hi:[1,0]
	v_pk_mul_f32 v[24:25], v[24:25], v[48:49] op_sel_hi:[1,0]
	v_pk_mul_f32 v[22:23], v[22:23], v[48:49] op_sel_hi:[1,0]
	v_pk_mul_f32 v[20:21], v[20:21], v[48:49] op_sel_hi:[1,0]
	v_pk_mul_f32 v[18:19], v[18:19], v[48:49] op_sel_hi:[1,0]
	v_pk_mul_f32 v[16:17], v[16:17], v[48:49] op_sel_hi:[1,0]
	v_xor_b32_e32 v48, 0x80000000, v1
	v_sub_f32_e32 v82, v82, v49
	v_sub_f32_e32 v83, v83, v49
	v_sub_f32_e32 v84, v84, v49
	v_sub_f32_e32 v85, v85, v49
	v_sub_f32_e32 v86, v86, v49
	v_sub_f32_e32 v87, v87, v49
	v_sub_f32_e32 v88, v88, v49
	v_sub_f32_e32 v89, v89, v49
	v_sub_f32_e32 v90, v90, v49
	v_sub_f32_e32 v91, v91, v49
	v_sub_f32_e32 v92, v92, v49
	v_sub_f32_e32 v93, v93, v49
	v_sub_f32_e32 v94, v94, v49
	v_sub_f32_e32 v95, v95, v49
	v_sub_f32_e32 v64, v64, v49
	v_sub_f32_e32 v65, v65, v49
	v_sub_f32_e32 v66, v66, v49
	v_sub_f32_e32 v67, v67, v49
	v_sub_f32_e32 v68, v68, v49
	v_sub_f32_e32 v69, v69, v49
	v_sub_f32_e32 v70, v70, v49
	v_sub_f32_e32 v71, v71, v49
	v_sub_f32_e32 v72, v72, v49
	v_sub_f32_e32 v73, v73, v49
	v_sub_f32_e32 v74, v74, v49
	v_sub_f32_e32 v75, v75, v49
	v_sub_f32_e32 v76, v76, v49
	v_sub_f32_e32 v77, v77, v49
	v_sub_f32_e32 v78, v78, v49
	v_sub_f32_e32 v79, v79, v49
	v_mov_b32_e32 v49, v48
	v_mov_b32_e32 v50, v48
	v_mov_b32_e32 v51, v48
	v_mov_b32_e32 v52, v48
	v_mov_b32_e32 v53, v48
	v_mov_b32_e32 v54, v48
	v_mov_b32_e32 v55, v48
	v_mov_b32_e32 v56, v48
	v_mov_b32_e32 v57, v48
	v_mov_b32_e32 v58, v48
	v_mov_b32_e32 v59, v48
	v_mov_b32_e32 v60, v48
	v_mov_b32_e32 v61, v48
	v_mov_b32_e32 v62, v48
	v_mov_b32_e32 v63, v48

; #define LAS __attribute__((address_space(3)))
; __device__ __forceinline__ void qk_tile(f32x16& s0, f32x16& s1, LAS unsigned char* kb, const bf16x8 (&qr)[6], const f32x16& negm, int r32, int hi) {
;     bf16x8 kf[12];
; #pragma unroll
;     for (int ks = 0; ks < 6; ++ks) { kf[2 * ks] = *(const LAS bf16x8*)(kb + r32 * KPT + ks * 32 + hi * 16); kf[2 * ks + 1] = *(const LAS bf16x8*)(kb + (32 + r32) * KPT + ks * 32 + hi * 16); }
;     __builtin_amdgcn_sched_barrier(0);
; #pragma unroll
;     for (int ks = 0; ks < 6; ++ks) {
;         s0 = __builtin_amdgcn_mfma_f32_32x32x16_bf16(kf[2 * ks], qr[ks], ks == 0 ? negm : s0, 0, 0, 0);
;         s1 = __builtin_amdgcn_mfma_f32_32x32x16_bf16(kf[2 * ks + 1], qr[ks], ks == 0 ? negm : s1, 0, 0, 0);
;     }
; }
; __device__ __forceinline__ void sm_pv(f32x16& s0, f32x16& s1, f32x16& o0, f32x16& o1, float& m_run, float& l_run, f32x16& negm, LAS unsigned char* vb, bool domask, int kbase, int qm, int r32, int hi) {
;     s16x4 vlo[8], vhh[8];
; #pragma unroll
;     for (int kk = 0; kk < 4; ++kk) { const int koff = 2 * (16 * kk + 4 * hi);
;         vlo[2 * kk] = *(const LAS s16x4*)(vb + r32 * VP + koff); vhh[2 * kk] = *(const LAS s16x4*)(vb + r32 * VP + koff + 16);
;         vlo[2 * kk + 1] = *(const LAS s16x4*)(vb + (32 + r32) * VP + koff); vhh[2 * kk + 1] = *(const LAS s16x4*)(vb + (32 + r32) * VP + koff + 16); }
;     __builtin_amdgcn_sched_barrier(0);
;     if (domask) {
;         const int kb0 = kbase + 4 * hi;
; #pragma unroll
;         for (int r = 0; r < 16; ++r) { const int kv = kb0 + (r & 3) + 8 * (r >> 2); if (kv > qm) s0[r] = -INFINITY; if (kv + 32 > qm) s1[r] = -INFINITY; }
;     }
.LBB0_453:
	s_or_b64 exec, exec, s[4:5]
	s_waitcnt vmcnt(4)
	v_perm_b32 v2, v190, v188, s94
	v_perm_b32 v3, v190, v188, s95
	ds_write2_b32 v254, v2, v3 offset0:128 offset1:162
	v_perm_b32 v2, v191, v189, s94
	v_perm_b32 v3, v191, v189, s95
	ds_write2_b32 v254, v2, v3 offset0:196 offset1:230
	s_waitcnt lgkmcnt(0)
	s_barrier
	s_andn2_b64 vcc, exec, s[44:45]
	s_cbranch_vccnz .LBB0_442
	s_cmp_gt_u32 s84, s57
	s_cselect_b32 s4, s79, 0
	s_lshl_b32 s4, s4, 6
	s_sub_i32 s5, 0xc0, s4
	s_add_i32 s4, s83, 64
	v_cmp_le_u32_e32 vcc, s4, v220
	s_and_saveexec_b64 s[44:45], vcc
	s_cbranch_execz .Latt_sk4
	ds_read_b128 v[2:5], v240 offset:13312
	ds_read_b128 v[6:9], v240 offset:13344
	ds_read_b128 v[10:13], v240 offset:19968
	ds_read_b128 v[136:139], v240 offset:20000
	ds_read_b128 v[140:143], v240 offset:13376
	ds_read_b128 v[144:147], v240 offset:13408
	ds_read_b128 v[148:151], v240 offset:20032
	ds_read_b128 v[152:155], v240 offset:20064
	ds_read_b128 v[156:159], v240 offset:13440
	ds_read_b128 v[160:163], v240 offset:13472
	ds_read_b128 v[222:225], v240 offset:20096
	ds_read_b128 v[226:229], v240 offset:20128
	s_waitcnt lgkmcnt(11)
	v_mfma_f32_32x32x16_bf16 v[80:95], v[2:5], v[96:99], v[48:63]
	s_add_i32 s4, s83, 0x7f
	v_cmp_gt_i32_e32 vcc, s4, v175
	s_waitcnt lgkmcnt(9)
	v_mfma_f32_32x32x16_bf16 v[64:79], v[10:13], v[96:99], v[48:63]
	v_mfma_f32_32x32x16_bf16 v[80:95], v[6:9], v[100:103], v[80:95]
	s_waitcnt lgkmcnt(8)
	v_mfma_f32_32x32x16_bf16 v[64:79], v[136:139], v[100:103], v[64:79]
	s_waitcnt lgkmcnt(7)
	v_mfma_f32_32x32x16_bf16 v[80:95], v[140:143], v[104:107], v[80:95]
	s_waitcnt lgkmcnt(5)
	v_mfma_f32_32x32x16_bf16 v[64:79], v[148:151], v[104:107], v[64:79]
	v_mfma_f32_32x32x16_bf16 v[80:95], v[144:147], v[108:111], v[80:95]
	ds_read2_b64 v[144:147], v250 offset0:68 offset1:70
	s_waitcnt lgkmcnt(5)
	v_mfma_f32_32x32x16_bf16 v[64:79], v[152:155], v[108:111], v[64:79]
	ds_read2_b64 v[152:155], v250 offset0:64 offset1:66
	ds_read2_b64 v[148:151], v251 offset0:96 offset1:98
	ds_read2_b64 v[140:143], v251 offset0:100 offset1:102
	ds_read2_b64 v[136:139], v250 offset0:72 offset1:74
	ds_read2_b64 v[10:13], v251 offset0:104 offset1:106
	ds_read2_b64 v[6:9], v250 offset0:76 offset1:78
	ds_read2_b64 v[2:5], v251 offset0:108 offset1:110
	s_waitcnt lgkmcnt(11)
	v_mfma_f32_32x32x16_bf16 v[80:95], v[156:159], v[112:115], v[80:95]
	s_waitcnt lgkmcnt(9)
	v_mfma_f32_32x32x16_bf16 v[64:79], v[222:225], v[112:115], v[64:79]
	v_mfma_f32_32x32x16_bf16 v[80:95], v[160:163], v[116:119], v[80:95]
	s_waitcnt lgkmcnt(8)
	v_mfma_f32_32x32x16_bf16 v[64:79], v[226:229], v[116:119], v[64:79]
	v_add_u32_e32 v128, s5, v14
	v_add_u32_e32 v188, s5, v15
	v_min_u32_e32 v128, 0x80ff, v128
	v_add_u32_e32 v190, 1, v188
	v_min_u32_e32 v188, 0x80ff, v188
	v_min_u32_e32 v190, 0x80ff, v190
	v_lshl_add_u32 v130, v128, 12, v238
	v_lshl_add_u32 v132, v128, 6, v239
	v_lshl_add_u32 v188, v188, 12, v174
	v_lshl_add_u32 v190, v190, 12, v174
	global_load_dwordx4 v[128:131], v130, s[98:99]
	s_nop 0
	global_load_dwordx4 v[132:135], v132, s[100:101]
	global_load_dwordx2 v[188:189], v188, s[98:99] offset:128
	global_load_dwordx2 v[190:191], v190, s[98:99] offset:128
	s_and_saveexec_b64 s[46:47], vcc
	s_cbranch_execz .LBB0_459
	v_add_u32_e32 v14, s83, v201
	v_add_u32_e32 v156, 0x60, v14
	v_add_u32_e32 v15, 64, v14
	v_cmp_le_u32_e64 s[4:5], v156, v219
	v_cmp_le_u32_e32 vcc, v15, v219
	s_nop 4
	v_cndmask_b32_e64 v64, v244, v64, s[4:5]
	v_cmp_lt_u32_e64 s[4:5], v15, v219
	v_add_u32_e32 v15, 0x61, v14
	v_cmp_le_u32_e64 s[6:7], v15, v219
	v_add_u32_e32 v15, 0x42, v14
	s_nop 0
	v_cndmask_b32_e64 v65, v244, v65, s[6:7]
	v_cmp_le_u32_e64 s[6:7], v15, v219
	v_add_u32_e32 v15, 0x62, v14
	v_cmp_le_u32_e64 s[8:9], v15, v219
	v_add_u32_e32 v15, 0x43, v14
	s_nop 0
	v_cndmask_b32_e64 v66, v244, v66, s[8:9]
	v_cmp_le_u32_e64 s[8:9], v15, v219
	v_add_u32_e32 v15, 0x63, v14
	v_cmp_le_u32_e64 s[10:11], v15, v219
	v_add_u32_e32 v15, 0x48, v14
	s_nop 0
	v_cndmask_b32_e64 v67, v244, v67, s[10:11]
	v_cmp_le_u32_e64 s[10:11], v15, v219
	v_add_u32_e32 v15, 0x68, v14
	v_cmp_le_u32_e64 s[12:13], v15, v219
	v_add_u32_e32 v15, 0x49, v14
	s_nop 0
	v_cndmask_b32_e64 v68, v244, v68, s[12:13]
	v_cmp_le_u32_e64 s[12:13], v15, v219
	v_add_u32_e32 v15, 0x69, v14
	v_cmp_le_u32_e64 s[14:15], v15, v219
	v_add_u32_e32 v15, 0x4a, v14
	s_nop 0
	v_cndmask_b32_e64 v69, v244, v69, s[14:15]
	v_cmp_le_u32_e64 s[14:15], v15, v219
	v_add_u32_e32 v15, 0x6a, v14
	v_cmp_le_u32_e64 s[16:17], v15, v219
	v_add_u32_e32 v15, 0x4b, v14
	s_nop 0
	v_cndmask_b32_e64 v70, v244, v70, s[16:17]
	v_cmp_le_u32_e64 s[16:17], v15, v219
	v_add_u32_e32 v15, 0x6b, v14
	v_cmp_le_u32_e64 s[18:19], v15, v219
	v_add_u32_e32 v15, 0x50, v14
	s_nop 0
	v_cndmask_b32_e64 v71, v244, v71, s[18:19]
	v_cmp_le_u32_e64 s[18:19], v15, v219
	v_add_u32_e32 v15, 0x70, v14
	v_cmp_le_u32_e64 s[20:21], v15, v219
	v_add_u32_e32 v15, 0x51, v14
	s_nop 0
	v_cndmask_b32_e64 v72, v244, v72, s[20:21]
	v_cmp_le_u32_e64 s[20:21], v15, v219
	v_add_u32_e32 v15, 0x71, v14
	v_cmp_le_u32_e64 s[22:23], v15, v219
	v_add_u32_e32 v15, 0x52, v14
	s_nop 0
	v_cndmask_b32_e64 v73, v244, v73, s[22:23]
	v_cmp_le_u32_e64 s[22:23], v15, v219
	v_add_u32_e32 v15, 0x72, v14
	v_cmp_le_u32_e64 s[24:25], v15, v219
	v_add_u32_e32 v15, 0x53, v14
	s_nop 0
	v_cndmask_b32_e64 v74, v244, v74, s[24:25]
	v_cmp_le_u32_e64 s[24:25], v15, v219
	v_add_u32_e32 v15, 0x73, v14
	v_cmp_le_u32_e64 s[26:27], v15, v219
	v_add_u32_e32 v15, 0x58, v14
	s_nop 0
	v_cndmask_b32_e64 v75, v244, v75, s[26:27]
	v_cmp_le_u32_e64 s[26:27], v15, v219
	v_add_u32_e32 v15, 0x78, v14
	v_cmp_le_u32_e64 s[28:29], v15, v219
	v_add_u32_e32 v15, 0x59, v14
	s_nop 0
	v_cndmask_b32_e64 v76, v244, v76, s[28:29]
	v_cmp_le_u32_e64 s[28:29], v15, v219
	v_add_u32_e32 v15, 0x79, v14
	v_cmp_le_u32_e64 s[30:31], v15, v219
	v_add_u32_e32 v15, 0x5a, v14
	s_nop 0
	v_cndmask_b32_e64 v77, v244, v77, s[30:31]
	v_cmp_le_u32_e64 s[30:31], v15, v219
	v_add_u32_e32 v15, 0x7a, v14
	v_cmp_le_u32_e64 s[34:35], v15, v219
	v_add_u32_e32 v15, 0x5b, v14
	v_add_u32_e32 v14, 0x7b, v14
	v_cndmask_b32_e64 v78, v244, v78, s[34:35]
	v_cmp_le_u32_e64 s[34:35], v15, v219
	v_cmp_gt_u32_e64 s[36:37], v14, v219
	s_and_saveexec_b64 s[40:41], s[36:37]
	v_mov_b32_e32 v79, s52
	s_or_b64 exec, exec, s[40:41]
	v_cndmask_b32_e64 v81, v244, v81, s[4:5]
	v_cndmask_b32_e32 v80, v244, v80, vcc
	v_cndmask_b32_e64 v82, v244, v82, s[6:7]
	v_cndmask_b32_e64 v83, v244, v83, s[8:9]
	v_cndmask_b32_e64 v84, v244, v84, s[10:11]
	v_cndmask_b32_e64 v85, v244, v85, s[12:13]
	v_cndmask_b32_e64 v86, v244, v86, s[14:15]
	v_cndmask_b32_e64 v87, v244, v87, s[16:17]
	v_cndmask_b32_e64 v88, v244, v88, s[18:19]
	v_cndmask_b32_e64 v89, v244, v89, s[20:21]
	v_cndmask_b32_e64 v90, v244, v90, s[22:23]
	v_cndmask_b32_e64 v91, v244, v91, s[24:25]
	v_cndmask_b32_e64 v92, v244, v92, s[26:27]
	v_cndmask_b32_e64 v93, v244, v93, s[28:29]
	v_cndmask_b32_e64 v94, v244, v94, s[30:31]
	v_cndmask_b32_e64 v95, v244, v95, s[34:35]
; __device__ __forceinline__ void sm_pv(f32x16& s0, f32x16& s1, f32x16& o0, f32x16& o1, float& m_run, float& l_run, f32x16& negm, LAS unsigned char* vb, bool domask, int kbase, int qm, int r32, int hi) {
;     ...
;     float ma = fmaxf(fmaxf(s0[0], s0[1]), s1[0]), mb = fmaxf(fmaxf(s0[2], s0[3]), s1[1]);
;     ma = fmaxf(fmaxf(ma, s1[2]), s1[3]);
; #pragma unroll
;     for (int r = 4; r < 16; r += 4) { ma = fmaxf(fmaxf(ma, s0[r]), s0[r + 1]); mb = fmaxf(fmaxf(mb, s0[r + 2]), s0[r + 3]); ma = fmaxf(fmaxf(ma, s1[r]), s1[r + 1]); mb = fmaxf(fmaxf(mb, s1[r + 2]), s1[r + 3]); }
;     float mx = fmaxf(ma, mb);
;     { const auto rr = __builtin_amdgcn_permlane32_swap(__float_as_uint(mx), __float_as_uint(mx), false, false); mx = fmaxf(__uint_as_float(rr[0]), __uint_as_float(rr[1])); }
;     if (__builtin_amdgcn_ballot_w64(mx > 8.0f) != 0ull) {
;         const float d = fmaxf(mx, 0.0f);
;         const float alpha = __builtin_amdgcn_exp2f(-d);
;         m_run += d; l_run *= alpha; o0 = o0 * alpha; o1 = o1 * alpha;
;         s0 = s0 - d; s1 = s1 - d;
; #pragma unroll
;         for (int r = 0; r < 16; ++r) negm[r] = -m_run;
;     }
.LBB0_459:
	s_or_b64 exec, exec, s[46:47]
	s_nop 0
	v_max_f32_e32 v14, v80, v81
	v_max3_f32 v15, v82, v83, v65
	v_max3_f32 v14, v14, v64, v66
	v_max3_f32 v14, v14, v67, v84
	v_max3_f32 v15, v15, v86, v87
	v_max3_f32 v14, v14, v85, v68
	v_max3_f32 v15, v15, v70, v71
	v_max3_f32 v14, v14, v69, v88
	v_max3_f32 v15, v15, v90, v91
	v_max3_f32 v14, v14, v89, v72
	v_max3_f32 v15, v15, v74, v75
	v_max3_f32 v14, v14, v73, v92
	v_max3_f32 v15, v15, v94, v95
	v_max3_f32 v14, v14, v93, v76
	v_max3_f32 v15, v15, v78, v79
	v_max3_f32 v14, v14, v77, v15
	v_mov_b32_e32 v15, v14
	s_nop 1
	v_permlane32_swap_b32_e32 v14, v15
	v_max_f32_e32 v14, v14, v15
	v_cmp_lt_f32_e32 vcc, s53, v14
	s_cbranch_vccz .LBB0_461
	v_max_f32_e32 v14, v14, v14
	v_max_f32_e32 v15, 0, v14
	v_exp_f32_e64 v14, -v15
	v_add_f32_e32 v1, v1, v15
	v_xor_b32_e32 v48, 0x80000000, v1
	v_sub_f32_e32 v80, v80, v15
	v_mul_f32_e32 v218, v218, v14
	v_pk_mul_f32 v[46:47], v[46:47], v[14:15] op_sel_hi:[1,0]
	v_pk_mul_f32 v[44:45], v[44:45], v[14:15] op_sel_hi:[1,0]
	v_pk_mul_f32 v[42:43], v[42:43], v[14:15] op_sel_hi:[1,0]
	v_pk_mul_f32 v[40:41], v[40:41], v[14:15] op_sel_hi:[1,0]
	v_pk_mul_f32 v[38:39], v[38:39], v[14:15] op_sel_hi:[1,0]
	v_pk_mul_f32 v[36:37], v[36:37], v[14:15] op_sel_hi:[1,0]
	v_pk_mul_f32 v[34:35], v[34:35], v[14:15] op_sel_hi:[1,0]
	v_pk_mul_f32 v[32:33], v[32:33], v[14:15] op_sel_hi:[1,0]
	v_pk_mul_f32 v[30:31], v[30:31], v[14:15] op_sel_hi:[1,0]
	v_pk_mul_f32 v[28:29], v[28:29], v[14:15] op_sel_hi:[1,0]
	v_pk_mul_f32 v[26:27], v[26:27], v[14:15] op_sel_hi:[1,0]
	v_pk_mul_f32 v[24:25], v[24:25], v[14:15] op_sel_hi:[1,0]
	v_pk_mul_f32 v[22:23], v[22:23], v[14:15] op_sel_hi:[1,0]
	v_pk_mul_f32 v[20:21], v[20:21], v[14:15] op_sel_hi:[1,0]
	v_pk_mul_f32 v[18:19], v[18:19], v[14:15] op_sel_hi:[1,0]
	v_pk_mul_f32 v[16:17], v[16:17], v[14:15] op_sel_hi:[1,0]
	v_sub_f32_e32 v81, v81, v15
	v_sub_f32_e32 v82, v82, v15
	v_sub_f32_e32 v83, v83, v15
	v_sub_f32_e32 v84, v84, v15
	v_sub_f32_e32 v85, v85, v15
	v_sub_f32_e32 v86, v86, v15
	v_sub_f32_e32 v87, v87, v15
	v_sub_f32_e32 v88, v88, v15
	v_sub_f32_e32 v89, v89, v15
	v_sub_f32_e32 v90, v90, v15
	v_sub_f32_e32 v91, v91, v15
	v_sub_f32_e32 v92, v92, v15
	v_sub_f32_e32 v93, v93, v15
	v_sub_f32_e32 v94, v94, v15
	v_sub_f32_e32 v95, v95, v15
	v_sub_f32_e32 v64, v64, v15
	v_sub_f32_e32 v65, v65, v15
	v_sub_f32_e32 v66, v66, v15
	v_sub_f32_e32 v67, v67, v15
	v_sub_f32_e32 v68, v68, v15
	v_sub_f32_e32 v69, v69, v15
	v_sub_f32_e32 v70, v70, v15
	v_sub_f32_e32 v71, v71, v15
	v_sub_f32_e32 v72, v72, v15
	v_sub_f32_e32 v73, v73, v15
	v_sub_f32_e32 v74, v74, v15
	v_sub_f32_e32 v75, v75, v15
	v_sub_f32_e32 v76, v76, v15
	v_sub_f32_e32 v77, v77, v15
	v_sub_f32_e32 v78, v78, v15
	v_sub_f32_e32 v79, v79, v15
	v_mov_b32_e32 v49, v48
	v_mov_b32_e32 v50, v48
	v_mov_b32_e32 v51, v48
	v_mov_b32_e32 v52, v48
	v_mov_b32_e32 v53, v48
	v_mov_b32_e32 v54, v48
	v_mov_b32_e32 v55, v48
	v_mov_b32_e32 v56, v48
	v_mov_b32_e32 v57, v48
	v_mov_b32_e32 v58, v48
	v_mov_b32_e32 v59, v48
	v_mov_b32_e32 v60, v48
	v_mov_b32_e32 v61, v48
	v_mov_b32_e32 v62, v48
	v_mov_b32_e32 v63, v48
